# layer-1 norm: row-invariant gain loads hoisted out of the row loop (same as layer-0 norm)
# baseline (speedup 1.0000x reference)
.LBB0_404:
	s_or_b64 exec, exec, s[4:5]
	s_ashr_i32 s4, s8, 6
	v_readlane_b32 s5, v253, 16
	s_add_i32 s4, s4, s5
	s_add_u32 s6, s0, 0x17400000
	s_addc_u32 s7, s1, 0
	s_cmpk_gt_i32 s4, 0x1fff
	v_and_b32_e32 v53, 63, v52
	s_cbranch_scc1 .LBB0_407
	v_and_b32_e32 v0, 64, v236
	v_add_u32_e32 v0, 64, v0
	s_waitcnt lgkmcnt(0)
	v_xor_b32_e32 v1, 1, v236
	v_cmp_lt_i32_e32 vcc, v1, v0
	v_readlane_b32 s8, v254, 31
	v_lshlrev_b32_e32 v160, 4, v53
	v_cndmask_b32_e32 v1, v236, v1, vcc
	v_lshlrev_b32_e32 v54, 2, v1
	v_xor_b32_e32 v1, 2, v236
	v_cmp_lt_i32_e32 vcc, v1, v0
	v_readlane_b32 s9, v254, 32
	s_ashr_i32 s5, s4, 31
	v_cndmask_b32_e32 v1, v236, v1, vcc
	v_lshlrev_b32_e32 v55, 2, v1
	v_xor_b32_e32 v1, 4, v236
	v_cmp_lt_i32_e32 vcc, v1, v0
	v_lshl_add_u64 v[4:5], s[8:9], 0, v[160:161]
	s_mov_b64 s[8:9], 0x1000
	v_cndmask_b32_e32 v1, v236, v1, vcc
	v_lshlrev_b32_e32 v56, 2, v1
	v_xor_b32_e32 v1, 8, v236
	v_cmp_lt_i32_e32 vcc, v1, v0
	v_lshl_add_u64 v[6:7], v[4:5], 0, s[8:9]
	s_mov_b64 s[8:9], 0x1400
	v_cndmask_b32_e32 v1, v236, v1, vcc
	v_lshlrev_b32_e32 v57, 2, v1
	v_xor_b32_e32 v1, 16, v236
	v_cmp_lt_i32_e32 vcc, v1, v0
	v_lshl_add_u64 v[8:9], v[4:5], 0, s[8:9]
	s_mov_b64 s[8:9], 0x1800
	v_cndmask_b32_e32 v1, v236, v1, vcc
	v_lshl_add_u64 v[10:11], v[4:5], 0, s[8:9]
	s_mov_b64 s[8:9], 0x1c00
	v_lshlrev_b32_e32 v58, 2, v1
	v_xor_b32_e32 v1, 32, v236
	v_lshl_add_u64 v[12:13], v[4:5], 0, s[8:9]
	s_lshl_b64 s[8:9], s[4:5], 12
	v_cmp_lt_i32_e32 vcc, v1, v0
	s_add_u32 s8, s6, s8
	v_lshlrev_b32_e32 v160, 3, v53
	v_cndmask_b32_e32 v0, v236, v1, vcc
	s_addc_u32 s9, s7, s9
	v_lshlrev_b32_e32 v59, 2, v0
	v_lshl_add_u64 v[14:15], s[8:9], 0, v[160:161]
	s_mov_b32 s5, s4
	global_load_dwordx4 v[104:107], v[4:5], off
	global_load_dwordx4 v[108:111], v[4:5], off offset:1024
	global_load_dwordx4 v[112:115], v[4:5], off offset:2048
	global_load_dwordx4 v[116:119], v[4:5], off offset:3072
	global_load_dwordx4 v[120:123], v[6:7], off
	global_load_dwordx4 v[124:127], v[8:9], off
	global_load_dwordx4 v[128:131], v[10:11], off
	global_load_dwordx4 v[132:135], v[12:13], off
.LBB0_406:
	v_add_co_u32_e32 v0, vcc, 0x2000000, v14
	s_add_i32 s5, s5, s86
	s_nop 0
	v_addc_co_u32_e32 v1, vcc, 0, v15, vcc
	flat_load_dwordx2 v[2:3], v[0:1]
	flat_load_dwordx2 v[28:29], v[0:1] offset:512
	flat_load_dwordx2 v[30:31], v[0:1] offset:1024
	flat_load_dwordx2 v[16:17], v[0:1] offset:1536
	flat_load_dwordx2 v[32:33], v[0:1] offset:2048
	flat_load_dwordx2 v[60:61], v[0:1] offset:2560
	flat_load_dwordx2 v[62:63], v[0:1] offset:3072
	s_nop 0
	flat_load_dwordx2 v[0:1], v[0:1] offset:3584
	s_cmpk_gt_i32 s5, 0x1fff
	s_waitcnt vmcnt(0) lgkmcnt(0)
	v_and_b32_e32 v49, 0xffff0000, v2
	v_and_b32_e32 v51, 0xffff0000, v3
	v_lshlrev_b32_e32 v48, 16, v2
	v_lshlrev_b32_e32 v50, 16, v3
	v_lshlrev_b32_e32 v21, 16, v0
	v_and_b32_e32 v19, 0xffff0000, v0
	v_mul_f32_e32 v0, v51, v51
	v_and_b32_e32 v45, 0xffff0000, v29
	v_and_b32_e32 v44, 0xffff0000, v28
	v_mul_f32_e32 v18, v49, v49
	v_lshlrev_b32_e32 v27, 16, v16
	v_and_b32_e32 v25, 0xffff0000, v16
	v_lshlrev_b32_e32 v22, 16, v17
	v_and_b32_e32 v23, 0xffff0000, v17
	v_lshlrev_b32_e32 v16, 16, v1
	v_and_b32_e32 v17, 0xffff0000, v1
	v_pk_fma_f32 v[0:1], v[50:51], v[50:51], v[0:1] op_sel_hi:[1,1,0]
	v_lshlrev_b32_e32 v47, 16, v29
	v_lshlrev_b32_e32 v46, 16, v28
	v_pk_mul_f32 v[2:3], v[44:45], v[44:45]
	v_pk_fma_f32 v[28:29], v[48:49], v[48:49], v[18:19] op_sel_hi:[1,1,0]
	v_pk_fma_f32 v[2:3], v[46:47], v[46:47], v[2:3]
	v_lshlrev_b32_e32 v40, 16, v30
	v_and_b32_e32 v41, 0xffff0000, v30
	v_lshlrev_b32_e32 v42, 16, v31
	v_and_b32_e32 v43, 0xffff0000, v31
	v_mov_b32_e32 v26, v28
	v_mov_b32_e32 v30, v0
	v_mov_b32_e32 v31, v27
	v_mul_f32_e32 v20, v25, v25
	v_pk_add_f32 v[0:1], v[28:29], v[0:1]
	v_pk_mul_f32 v[28:29], v[26:27], v[30:31]
	v_pk_add_f32 v[2:3], v[2:3], v[2:3] op_sel:[0,1] op_sel_hi:[1,0]
	v_mov_b32_e32 v1, v29
	v_mov_b32_e32 v3, v20
	v_pk_add_f32 v[0:1], v[0:1], v[2:3]
	v_mul_f32_e32 v2, v41, v41
	v_mul_f32_e32 v18, v43, v43
	v_mul_f32_e32 v24, v22, v22
	v_mul_f32_e32 v34, v23, v23
	v_pk_fma_f32 v[2:3], v[40:41], v[40:41], v[2:3] op_sel_hi:[1,1,0]
	v_pk_fma_f32 v[28:29], v[42:43], v[42:43], v[18:19] op_sel_hi:[1,1,0]
	v_mov_b32_e32 v3, v24
	v_mov_b32_e32 v29, v34
	v_pk_add_f32 v[2:3], v[2:3], v[28:29]
	v_and_b32_e32 v37, 0xffff0000, v33
	v_and_b32_e32 v36, 0xffff0000, v32
	v_pk_add_f32 v[0:1], v[0:1], v[2:3]
	v_lshlrev_b32_e32 v39, 16, v33
	v_lshlrev_b32_e32 v38, 16, v32
	v_pk_mul_f32 v[2:3], v[36:37], v[36:37]
	v_and_b32_e32 v33, 0xffff0000, v61
	v_pk_fma_f32 v[2:3], v[38:39], v[38:39], v[2:3]
	v_and_b32_e32 v32, 0xffff0000, v60
	v_pk_add_f32 v[2:3], v[2:3], v[2:3] op_sel:[0,1] op_sel_hi:[1,0]
	v_lshlrev_b32_e32 v35, 16, v61
	v_lshlrev_b32_e32 v34, 16, v60
	v_pk_mul_f32 v[28:29], v[32:33], v[32:33]
	v_pk_add_f32 v[0:1], v[0:1], v[0:1] op_sel:[0,1] op_sel_hi:[1,0]
	v_pk_fma_f32 v[60:61], v[34:35], v[34:35], v[28:29]
	v_lshlrev_b32_e32 v28, 16, v62
	v_and_b32_e32 v29, 0xffff0000, v62
	v_lshlrev_b32_e32 v30, 16, v63
	v_and_b32_e32 v31, 0xffff0000, v63
	v_mov_b32_e32 v20, v0
	v_mov_b32_e32 v62, v2
	v_mov_b32_e32 v63, v21
	v_pk_add_f32 v[0:1], v[0:1], v[2:3]
	v_pk_mul_f32 v[2:3], v[20:21], v[62:63]
	v_mul_f32_e32 v18, v19, v19
	v_mov_b32_e32 v1, v3
	v_pk_add_f32 v[2:3], v[60:61], v[60:61] op_sel:[0,1] op_sel_hi:[1,0]
	v_mul_f32_e32 v24, v16, v16
	v_mov_b32_e32 v3, v18
	v_pk_add_f32 v[0:1], v[0:1], v[2:3]
	v_mul_f32_e32 v2, v29, v29
	v_mul_f32_e32 v18, v31, v31
	v_mul_f32_e32 v26, v17, v17
	v_pk_fma_f32 v[2:3], v[28:29], v[28:29], v[2:3] op_sel_hi:[1,1,0]
	v_pk_fma_f32 v[60:61], v[30:31], v[30:31], v[18:19] op_sel_hi:[1,1,0]
	v_mov_b32_e32 v3, v24
	v_mov_b32_e32 v61, v26
	v_pk_add_f32 v[2:3], v[2:3], v[60:61]
	v_mov_b32_e32 v24, v27
	v_pk_add_f32 v[0:1], v[0:1], v[2:3]
	v_mov_b32_e32 v18, v21
	v_add_f32_e32 v0, v0, v1
	ds_bpermute_b32 v1, v54, v0
	s_waitcnt lgkmcnt(0)
	v_add_f32_e32 v0, v0, v1
	ds_bpermute_b32 v1, v55, v0
	s_waitcnt lgkmcnt(0)
	v_add_f32_e32 v0, v0, v1
	ds_bpermute_b32 v1, v56, v0
	s_waitcnt lgkmcnt(0)
	v_add_f32_e32 v0, v0, v1
	ds_bpermute_b32 v1, v57, v0
	s_waitcnt lgkmcnt(0)
	v_add_f32_e32 v0, v0, v1
	ds_bpermute_b32 v1, v58, v0
	s_waitcnt lgkmcnt(0)
	v_add_f32_e32 v0, v0, v1
	ds_bpermute_b32 v1, v59, v0
	s_waitcnt lgkmcnt(0)
	v_add_f32_e32 v0, v0, v1
	v_fmamk_f32 v0, v0, 0x3a000000, v195
	v_rsq_f32_e32 v20, v0
	v_mov_b32_e32 v0, v104
	v_mov_b32_e32 v1, v105
	v_mov_b32_e32 v2, v106
	v_mov_b32_e32 v3, v107
	v_pk_mul_f32 v[48:49], v[20:21], v[48:49] op_sel_hi:[0,1]
	v_pk_mul_f32 v[50:51], v[20:21], v[50:51] op_sel_hi:[0,1]
	v_pk_mul_f32 v[40:41], v[20:21], v[40:41] op_sel_hi:[0,1]
	v_pk_mul_f32 v[42:43], v[20:21], v[42:43] op_sel_hi:[0,1]
	v_pk_mul_f32 v[24:25], v[24:25], v[20:21] op_sel_hi:[1,0]
	v_pk_mul_f32 v[22:23], v[22:23], v[20:21] op_sel_hi:[1,0]
	v_pk_mul_f32 v[18:19], v[18:19], v[20:21] op_sel_hi:[1,0]
	v_pk_mul_f32 v[16:17], v[16:17], v[20:21] op_sel_hi:[1,0]
	s_nop 0
	v_pk_mul_f32 v[2:3], v[2:3], v[50:51]
	v_pk_mul_f32 v[0:1], v[0:1], v[48:49]
	v_mov_b32_e32 v48, v46
	v_cvt_pk_bf16_f32 v0, v0, v1
	v_cvt_pk_bf16_f32 v1, v2, v3
	flat_store_dwordx2 v[14:15], v[0:1]
	v_mov_b32_e32 v0, v108
	v_mov_b32_e32 v1, v109
	v_mov_b32_e32 v2, v110
	v_mov_b32_e32 v3, v111
	v_mov_b32_e32 v49, v44
	v_mov_b32_e32 v44, v47
	v_pk_mul_f32 v[48:49], v[20:21], v[48:49] op_sel_hi:[0,1]
	v_pk_mul_f32 v[44:45], v[20:21], v[44:45] op_sel_hi:[0,1]
	s_nop 0
	v_pk_mul_f32 v[2:3], v[2:3], v[44:45]
	v_pk_mul_f32 v[0:1], v[0:1], v[48:49]
	s_nop 0
	v_cvt_pk_bf16_f32 v0, v0, v1
	v_cvt_pk_bf16_f32 v1, v2, v3
	flat_store_dwordx2 v[14:15], v[0:1] offset:512
	v_mov_b32_e32 v0, v112
	v_mov_b32_e32 v1, v113
	v_mov_b32_e32 v2, v114
	v_mov_b32_e32 v3, v115
	s_nop 0
	v_pk_mul_f32 v[2:3], v[2:3], v[42:43]
	v_pk_mul_f32 v[0:1], v[0:1], v[40:41]
	s_nop 0
	v_cvt_pk_bf16_f32 v0, v0, v1
	v_cvt_pk_bf16_f32 v1, v2, v3
	flat_store_dwordx2 v[14:15], v[0:1] offset:1024
	v_mov_b32_e32 v0, v116
	v_mov_b32_e32 v1, v117
	v_mov_b32_e32 v2, v118
	v_mov_b32_e32 v3, v119
	s_nop 0
	v_pk_mul_f32 v[2:3], v[2:3], v[22:23]
	v_pk_mul_f32 v[0:1], v[0:1], v[24:25]
	v_mov_b32_e32 v22, v38
	v_cvt_pk_bf16_f32 v0, v0, v1
	v_cvt_pk_bf16_f32 v1, v2, v3
	flat_store_dwordx2 v[14:15], v[0:1] offset:1536
	v_mov_b32_e32 v0, v120
	v_mov_b32_e32 v1, v121
	v_mov_b32_e32 v2, v122
	v_mov_b32_e32 v3, v123
	v_mov_b32_e32 v23, v36
	v_mov_b32_e32 v36, v39
	v_pk_mul_f32 v[22:23], v[20:21], v[22:23] op_sel_hi:[0,1]
	v_pk_mul_f32 v[24:25], v[20:21], v[36:37] op_sel_hi:[0,1]
	s_nop 0
	v_pk_mul_f32 v[2:3], v[2:3], v[24:25]
	v_pk_mul_f32 v[0:1], v[0:1], v[22:23]
	v_mov_b32_e32 v22, v34
	v_cvt_pk_bf16_f32 v0, v0, v1
	v_cvt_pk_bf16_f32 v1, v2, v3
	flat_store_dwordx2 v[14:15], v[0:1] offset:2048
	v_mov_b32_e32 v0, v124
	v_mov_b32_e32 v1, v125
	v_mov_b32_e32 v2, v126
	v_mov_b32_e32 v3, v127
	v_mov_b32_e32 v23, v32
	v_mov_b32_e32 v32, v35
	v_pk_mul_f32 v[22:23], v[20:21], v[22:23] op_sel_hi:[0,1]
	v_pk_mul_f32 v[24:25], v[20:21], v[32:33] op_sel_hi:[0,1]
	s_nop 0
	v_pk_mul_f32 v[2:3], v[2:3], v[24:25]
	v_pk_mul_f32 v[0:1], v[0:1], v[22:23]
	v_pk_mul_f32 v[22:23], v[20:21], v[28:29] op_sel_hi:[0,1]
	v_cvt_pk_bf16_f32 v0, v0, v1
	v_cvt_pk_bf16_f32 v1, v2, v3
	flat_store_dwordx2 v[14:15], v[0:1] offset:2560
	v_mov_b32_e32 v0, v128
	v_mov_b32_e32 v1, v129
	v_mov_b32_e32 v2, v130
	v_mov_b32_e32 v3, v131
	v_pk_mul_f32 v[24:25], v[20:21], v[30:31] op_sel_hi:[0,1]
	s_nop 0
	v_pk_mul_f32 v[2:3], v[24:25], v[2:3]
	v_pk_mul_f32 v[0:1], v[22:23], v[0:1]
	s_nop 0
	v_cvt_pk_bf16_f32 v0, v0, v1
	v_cvt_pk_bf16_f32 v1, v2, v3
	flat_store_dwordx2 v[14:15], v[0:1] offset:3072
	v_mov_b32_e32 v0, v132
	v_mov_b32_e32 v1, v133
	v_mov_b32_e32 v2, v134
	v_mov_b32_e32 v3, v135
	s_nop 0
	v_pk_mul_f32 v[2:3], v[16:17], v[2:3]
	v_pk_mul_f32 v[0:1], v[18:19], v[0:1]
	s_nop 0
	v_cvt_pk_bf16_f32 v0, v0, v1
	v_cvt_pk_bf16_f32 v1, v2, v3
	flat_store_dwordx2 v[14:15], v[0:1] offset:3584
	v_lshl_add_u64 v[14:15], v[14:15], 0, s[62:63]
	s_cbranch_scc0 .LBB0_406
